# v26 + nt on the f32 input-row loads of the two pre-GEMM norm passes
# speedup vs baseline: 1.0035x; 1.0035x over previous
; __device__ __forceinline__ float bflo(unsigned w) { return __uint_as_float(w << 16); }
; __device__ __forceinline__ float bfhi(unsigned w) { return __uint_as_float(w & 0xffff0000u); }
; __device__ __forceinline__ unsigned pkbf(float lo, float hi) { return pg8::cvt_pk_bf16(lo, hi); }
; __device__ __forceinline__ void norm_row(const float* src, const bf16_t* add, const float* gain, bf16_t* ob, float* of, int lane) {
;     f32x4 v[4]; float s = 0.f;
; #pragma unroll
;     for (int j = 0; j < 4; ++j) { v[j] = *((const f32x4*)src + lane + 64 * j);
;         if (add) { const u32x2 d = *((const u32x2*)add + lane + 64 * j); v[j][0] += bflo(d.x); v[j][1] += bfhi(d.x); v[j][2] += bflo(d.y); v[j][3] += bfhi(d.y); }
;         s += (v[j][0] * v[j][0] + v[j][1] * v[j][1]) + (v[j][2] * v[j][2] + v[j][3] * v[j][3]); }
;     const float rstd = 1.0f / sqrtf(wave_sum(s) * (1.f / DM) + NORM_EPS);
; #pragma unroll
;     for (int j = 0; j < 4; ++j) { const f32x4 g = *((const f32x4*)gain + lane + 64 * j); const f32x4 o = v[j] * rstd * g;
;         if (ob) { u32x2 w; w.x = pkbf(o[0], o[1]); w.y = pkbf(o[2], o[3]); *((u32x2*)ob + lane + 64 * j) = w; }
;         else *((f32x4*)of + lane + 64 * j) = o; }
; }
.LBB0_71:
	s_add_i32 s0, s6, 0xffff8000
	s_cmp_lt_i32 s6, 0x8000
	s_cselect_b32 s1, s7, 0
	s_cselect_b32 s0, s6, s0
	s_cselect_b32 s8, s17, s19
	s_cselect_b32 s9, s16, s18
	s_lshl_b64 s[0:1], s[0:1], 12
	s_add_u32 s0, s9, s0
	s_addc_u32 s1, s8, s1
	global_load_dwordx4 v[14:17], v11, s[0:1] nt
	global_load_dwordx4 v[18:21], v11, s[0:1] offset:1024 nt
	global_load_dwordx4 v[22:25], v11, s[0:1] offset:2048 nt
	global_load_dwordx4 v[26:29], v11, s[0:1] offset:3072 nt
	global_load_dwordx4 v[30:33], v[2:3], off
	s_add_u32 s6, s6, s88
	s_addc_u32 s7, s7, s89
	s_cmp_gt_i32 s6, 0xbfff
	s_waitcnt vmcnt(4)
	v_pk_mul_f32 v[34:35], v[16:17], v[16:17]
	v_pk_mul_f32 v[36:37], v[14:15], v[14:15]
	s_waitcnt vmcnt(3)
	v_pk_mul_f32 v[38:39], v[20:21], v[20:21]
	v_pk_mul_f32 v[40:41], v[18:19], v[18:19]
	v_pk_mov_b32 v[46:47], v[36:37], v[34:35] op_sel:[1,0]
	v_mov_b32_e32 v37, v35
	v_pk_mov_b32 v[34:35], v[40:41], v[38:39] op_sel:[1,0]
	v_mov_b32_e32 v41, v39
	s_waitcnt vmcnt(1)
	v_mul_f32_e32 v45, v26, v26
	v_mul_f32_e32 v42, v23, v23
	v_mul_f32_e32 v44, v25, v25
	v_pk_add_f32 v[36:37], v[46:47], v[36:37]
	v_pk_add_f32 v[34:35], v[34:35], v[40:41]
	v_mul_f32_e32 v48, v27, v27
	v_mul_f32_e32 v49, v28, v28
	v_mul_f32_e32 v50, v29, v29
	v_pk_fma_f32 v[38:39], v[22:23], v[22:23], v[42:43] op_sel_hi:[1,1,0]
	v_pk_fma_f32 v[42:43], v[24:25], v[24:25], v[44:45] op_sel_hi:[1,1,0]
	v_pk_add_f32 v[36:37], v[36:37], v[36:37] op_sel:[0,1] op_sel_hi:[1,0]
	v_pk_add_f32 v[34:35], v[34:35], v[34:35] op_sel:[0,1] op_sel_hi:[1,0]
	v_mov_b32_e32 v39, v49
	v_mov_b32_e32 v43, v50
	v_mov_b32_e32 v37, v45
	v_mov_b32_e32 v35, v48
	v_pk_add_f32 v[38:39], v[38:39], v[42:43]
	v_pk_add_f32 v[34:35], v[36:37], v[34:35]
	s_nop 0
	v_pk_add_f32 v[34:35], v[34:35], v[38:39]
	s_nop 0
	v_add_f32_e32 v34, v34, v35
	ds_bpermute_b32 v35, v1, v34
	s_waitcnt lgkmcnt(0)
	v_add_f32_e32 v34, v34, v35
	ds_bpermute_b32 v35, v6, v34
	s_waitcnt lgkmcnt(0)
	v_add_f32_e32 v34, v34, v35
	ds_bpermute_b32 v35, v7, v34
	s_waitcnt lgkmcnt(0)
	v_add_f32_e32 v34, v34, v35
	ds_bpermute_b32 v35, v8, v34
	s_waitcnt lgkmcnt(0)
	v_add_f32_e32 v34, v34, v35
	ds_bpermute_b32 v35, v9, v34
	s_waitcnt lgkmcnt(0)
	v_add_f32_e32 v34, v34, v35
	ds_bpermute_b32 v35, v10, v34
	s_waitcnt lgkmcnt(0)
	v_add_f32_e32 v34, v34, v35
	v_fmamk_f32 v34, v34, 0x3a800000, v12
	v_mul_f32_e32 v35, 0x4f800000, v34
	v_cmp_gt_f32_e32 vcc, s3, v34
	s_nop 1
	v_cndmask_b32_e32 v34, v34, v35, vcc
	v_sqrt_f32_e32 v35, v34
	s_nop 0
	v_add_u32_e32 v36, -1, v35
	v_add_u32_e32 v37, 1, v35
	v_fma_f32 v38, -v36, v35, v34
	v_fma_f32 v39, -v37, v35, v34
	v_cmp_ge_f32_e64 s[0:1], 0, v38
	s_nop 1
	v_cndmask_b32_e64 v35, v35, v36, s[0:1]
	v_cmp_lt_f32_e64 s[0:1], 0, v39
	s_nop 1
	v_cndmask_b32_e64 v35, v35, v37, s[0:1]
	v_mul_f32_e32 v36, 0x37800000, v35
	v_cndmask_b32_e32 v35, v35, v36, vcc
	v_cmp_class_f32_e32 vcc, v34, v13
	s_nop 1
	v_cndmask_b32_e32 v34, v35, v34, vcc
	v_div_scale_f32 v35, s[0:1], v34, v34, 1.0
	v_rcp_f32_e32 v37, v35
	v_div_scale_f32 v36, vcc, 1.0, v34, 1.0
	v_fma_f32 v38, -v35, v37, 1.0
	v_fmac_f32_e32 v37, v38, v37
	v_mul_f32_e32 v38, v36, v37
	v_fma_f32 v39, -v35, v38, v36
	v_fmac_f32_e32 v38, v39, v37
	v_fma_f32 v35, -v35, v38, v36
	v_div_fmas_f32 v35, v35, v37, v38
	v_div_fixup_f32 v34, v35, v34, 1.0
	v_pk_mul_f32 v[14:15], v[14:15], v[34:35] op_sel_hi:[1,0]
	v_pk_mul_f32 v[16:17], v[16:17], v[34:35] op_sel_hi:[1,0]
	s_waitcnt vmcnt(0)
	v_pk_mul_f32 v[14:15], v[30:31], v[14:15]
	v_pk_mul_f32 v[16:17], v[32:33], v[16:17]
	v_cvt_pk_bf16_f32 v14, v14, v15
	v_pk_mul_f32 v[18:19], v[18:19], v[34:35] op_sel_hi:[1,0]
	v_cvt_pk_bf16_f32 v15, v16, v17
	global_store_dwordx2 v[4:5], v[14:15], off
	global_load_dwordx4 v[14:17], v[2:3], off offset:1024
	v_pk_mul_f32 v[20:21], v[20:21], v[34:35] op_sel_hi:[1,0]
	s_waitcnt vmcnt(0)
	v_pk_mul_f32 v[14:15], v[14:15], v[18:19]
	v_pk_mul_f32 v[16:17], v[16:17], v[20:21]
	v_cvt_pk_bf16_f32 v14, v14, v15
	v_pk_mul_f32 v[18:19], v[22:23], v[34:35] op_sel_hi:[1,0]
	v_cvt_pk_bf16_f32 v15, v16, v17
	global_store_dwordx2 v[4:5], v[14:15], off offset:512
	global_load_dwordx4 v[14:17], v[2:3], off offset:2048
	v_pk_mul_f32 v[20:21], v[24:25], v[34:35] op_sel_hi:[1,0]
	s_waitcnt vmcnt(0)
	v_pk_mul_f32 v[14:15], v[14:15], v[18:19]
	v_pk_mul_f32 v[16:17], v[16:17], v[20:21]
	v_cvt_pk_bf16_f32 v14, v14, v15
	v_pk_mul_f32 v[18:19], v[26:27], v[34:35] op_sel_hi:[1,0]
	v_cvt_pk_bf16_f32 v15, v16, v17
	global_store_dwordx2 v[4:5], v[14:15], off offset:1024
	global_load_dwordx4 v[14:17], v[2:3], off offset:3072
	v_pk_mul_f32 v[20:21], v[28:29], v[34:35] op_sel_hi:[1,0]
	s_waitcnt vmcnt(0)
	v_pk_mul_f32 v[14:15], v[18:19], v[14:15]
	v_pk_mul_f32 v[16:17], v[20:21], v[16:17]
	v_cvt_pk_bf16_f32 v14, v14, v15
	s_nop 0
	v_cvt_pk_bf16_f32 v15, v16, v17
	global_store_dwordx2 v[4:5], v[14:15], off offset:1536
	v_lshl_add_u64 v[4:5], v[4:5], 0, s[4:5]
	s_cbranch_scc0 .LBB0_71

; __device__ __forceinline__ float bflo(unsigned w) { return __uint_as_float(w << 16); }
; __device__ __forceinline__ float bfhi(unsigned w) { return __uint_as_float(w & 0xffff0000u); }
; __device__ __forceinline__ unsigned pkbf(float lo, float hi) { return pg8::cvt_pk_bf16(lo, hi); }
; __device__ __forceinline__ void norm_row(const float* src, const bf16_t* add, const float* gain, bf16_t* ob, float* of, int lane) {
;     f32x4 v[4]; float s = 0.f;
; #pragma unroll
;     for (int j = 0; j < 4; ++j) { v[j] = *((const f32x4*)src + lane + 64 * j);
;         if (add) { const u32x2 d = *((const u32x2*)add + lane + 64 * j); v[j][0] += bflo(d.x); v[j][1] += bfhi(d.x); v[j][2] += bflo(d.y); v[j][3] += bfhi(d.y); }
;         s += (v[j][0] * v[j][0] + v[j][1] * v[j][1]) + (v[j][2] * v[j][2] + v[j][3] * v[j][3]); }
;     const float rstd = 1.0f / sqrtf(wave_sum(s) * (1.f / DM) + NORM_EPS);
; #pragma unroll
;     for (int j = 0; j < 4; ++j) { const f32x4 g = *((const f32x4*)gain + lane + 64 * j); const f32x4 o = v[j] * rstd * g;
;         if (ob) { u32x2 w; w.x = pkbf(o[0], o[1]); w.y = pkbf(o[2], o[3]); *((u32x2*)ob + lane + 64 * j) = w; }
;         else *((f32x4*)of + lane + 64 * j) = o; }
; }
.LBB0_284:
	s_add_i32 s12, s6, 0xffff8000
	v_add_co_u32_e64 v16, s[0:1], s8, v2
	v_add_co_u32_e32 v14, vcc, s3, v2
	s_nop 0
	v_addc_co_u32_e64 v17, s[0:1], -1, v3, s[0:1]
	s_cmp_lt_i32 s6, 0x8000
	v_addc_co_u32_e32 v15, vcc, -1, v3, vcc
	s_cselect_b32 s1, s7, 0
	s_cselect_b32 s0, s6, s12
	global_load_dwordx2 v[34:35], v[14:15], off
	global_load_dwordx2 v[36:37], v[16:17], off offset:-3584
	s_cselect_b32 s12, s17, s19
	s_cselect_b32 s13, s16, s18
	s_lshl_b64 s[0:1], s[0:1], 12
	global_load_dwordx2 v[38:39], v[16:17], off offset:-3072
	global_load_dwordx2 v[40:41], v[16:17], off offset:-2560
	s_add_u32 s0, s13, s0
	s_addc_u32 s1, s12, s1
	global_load_dwordx4 v[14:17], v10, s[0:1] nt
	global_load_dwordx4 v[18:21], v10, s[0:1] offset:1024 nt
	global_load_dwordx4 v[22:25], v10, s[0:1] offset:2048 nt
	global_load_dwordx4 v[26:29], v10, s[0:1] offset:3072 nt
	global_load_dwordx4 v[30:33], v[0:1], off
	s_add_u32 s6, s6, s88
	s_addc_u32 s7, s7, s89
	s_cmp_gt_i32 s6, 0xbfff
	s_waitcnt vmcnt(8)
	v_lshlrev_b32_e32 v42, 16, v34
	v_and_b32_e32 v43, 0xffff0000, v34
	v_lshlrev_b32_e32 v34, 16, v35
	v_and_b32_e32 v35, 0xffff0000, v35
	s_waitcnt vmcnt(7)
	v_lshlrev_b32_e32 v44, 16, v36
	v_and_b32_e32 v45, 0xffff0000, v36
	v_lshlrev_b32_e32 v36, 16, v37
	v_and_b32_e32 v37, 0xffff0000, v37
	s_waitcnt vmcnt(5)
	v_lshlrev_b32_e32 v48, 16, v40
	v_and_b32_e32 v49, 0xffff0000, v40
	v_lshlrev_b32_e32 v40, 16, v41
	v_and_b32_e32 v41, 0xffff0000, v41
	s_waitcnt vmcnt(4)
	v_pk_add_f32 v[14:15], v[14:15], v[42:43]
	v_pk_add_f32 v[16:17], v[16:17], v[34:35]
	s_waitcnt vmcnt(3)
	v_pk_add_f32 v[18:19], v[18:19], v[44:45]
	v_pk_add_f32 v[20:21], v[20:21], v[36:37]
	v_lshlrev_b32_e32 v46, 16, v38
	v_and_b32_e32 v47, 0xffff0000, v38
	v_lshlrev_b32_e32 v38, 16, v39
	v_and_b32_e32 v39, 0xffff0000, v39
	s_waitcnt vmcnt(1)
	v_pk_add_f32 v[28:29], v[28:29], v[40:41]
	v_mov_b32_e32 v36, v15
	v_mov_b32_e32 v37, v17
	v_mov_b32_e32 v40, v19
	v_mov_b32_e32 v41, v21
	v_pk_add_f32 v[22:23], v[22:23], v[46:47]
	v_pk_add_f32 v[24:25], v[24:25], v[38:39]
	v_mov_b32_e32 v34, v14
	v_mov_b32_e32 v35, v16
	v_mov_b32_e32 v38, v18
	v_mov_b32_e32 v39, v20
	v_pk_mul_f32 v[36:37], v[36:37], v[36:37]
	v_pk_mul_f32 v[40:41], v[40:41], v[40:41]
	v_pk_add_f32 v[26:27], v[26:27], v[48:49]
	v_mul_f32_e32 v42, v23, v23
	v_mul_f32_e32 v44, v25, v25
	v_pk_fma_f32 v[34:35], v[34:35], v[34:35], v[36:37]
	v_pk_fma_f32 v[36:37], v[38:39], v[38:39], v[40:41]
	v_pk_mul_f32 v[46:47], v[26:27], v[26:27]
	v_pk_mul_f32 v[48:49], v[28:29], v[28:29]
	v_pk_fma_f32 v[42:43], v[22:23], v[22:23], v[42:43] op_sel_hi:[1,1,0]
	v_pk_fma_f32 v[44:45], v[24:25], v[24:25], v[44:45] op_sel_hi:[1,1,0]
	v_pk_add_f32 v[34:35], v[34:35], v[34:35] op_sel:[0,1] op_sel_hi:[1,0]
	v_pk_add_f32 v[36:37], v[36:37], v[36:37] op_sel:[0,1] op_sel_hi:[1,0]
	v_mov_b32_e32 v43, v48
	v_mov_b32_e32 v45, v49
	v_mov_b32_e32 v35, v46
	v_mov_b32_e32 v37, v47
	v_pk_add_f32 v[38:39], v[42:43], v[44:45]
	v_pk_add_f32 v[34:35], v[34:35], v[36:37]
	s_nop 0
	v_pk_add_f32 v[34:35], v[34:35], v[38:39]
	s_nop 0
	v_add_f32_e32 v13, v34, v35
	ds_bpermute_b32 v34, v4, v13
	s_waitcnt lgkmcnt(0)
	v_add_f32_e32 v13, v13, v34
	ds_bpermute_b32 v34, v5, v13
	s_waitcnt lgkmcnt(0)
	v_add_f32_e32 v13, v13, v34
	ds_bpermute_b32 v34, v6, v13
	s_waitcnt lgkmcnt(0)
	v_add_f32_e32 v13, v13, v34
	ds_bpermute_b32 v34, v7, v13
	s_waitcnt lgkmcnt(0)
	v_add_f32_e32 v13, v13, v34
	ds_bpermute_b32 v34, v8, v13
	s_waitcnt lgkmcnt(0)
	v_add_f32_e32 v13, v13, v34
	ds_bpermute_b32 v34, v9, v13
	s_waitcnt lgkmcnt(0)
	v_add_f32_e32 v13, v13, v34
	v_fmamk_f32 v13, v13, 0x3a800000, v11
	v_mul_f32_e32 v34, 0x4f800000, v13
	v_cmp_gt_f32_e32 vcc, s9, v13
	s_nop 1
	v_cndmask_b32_e32 v13, v13, v34, vcc
	v_sqrt_f32_e32 v34, v13
	s_nop 0
	v_add_u32_e32 v35, -1, v34
	v_add_u32_e32 v36, 1, v34
	v_fma_f32 v37, -v35, v34, v13
	v_fma_f32 v38, -v36, v34, v13
	v_cmp_ge_f32_e64 s[0:1], 0, v37
	s_nop 1
	v_cndmask_b32_e64 v34, v34, v35, s[0:1]
	v_cmp_lt_f32_e64 s[0:1], 0, v38
	s_nop 1
	v_cndmask_b32_e64 v34, v34, v36, s[0:1]
	v_mul_f32_e32 v35, 0x37800000, v34
	v_cndmask_b32_e32 v34, v34, v35, vcc
	v_cmp_class_f32_e32 vcc, v13, v12
	s_nop 1
	v_cndmask_b32_e32 v13, v34, v13, vcc
	v_div_scale_f32 v34, s[0:1], v13, v13, 1.0
	v_rcp_f32_e32 v36, v34
	v_div_scale_f32 v35, vcc, 1.0, v13, 1.0
	v_fma_f32 v37, -v34, v36, 1.0
	v_fmac_f32_e32 v36, v37, v36
	v_mul_f32_e32 v37, v35, v36
	v_fma_f32 v38, -v34, v37, v35
	v_fmac_f32_e32 v37, v38, v36
	v_fma_f32 v34, -v34, v37, v35
	v_div_fmas_f32 v34, v34, v36, v37
	v_div_fixup_f32 v34, v34, v13, 1.0
	v_pk_mul_f32 v[14:15], v[14:15], v[34:35] op_sel_hi:[1,0]
	v_pk_mul_f32 v[16:17], v[16:17], v[34:35] op_sel_hi:[1,0]
	s_waitcnt vmcnt(0)
	v_pk_mul_f32 v[14:15], v[30:31], v[14:15]
	v_pk_mul_f32 v[16:17], v[32:33], v[16:17]
	v_cvt_pk_bf16_f32 v14, v14, v15
	v_pk_mul_f32 v[18:19], v[18:19], v[34:35] op_sel_hi:[1,0]
	v_cvt_pk_bf16_f32 v15, v16, v17
	global_store_dwordx2 v[2:3], v[14:15], off
	global_load_dwordx4 v[14:17], v[0:1], off offset:1024
	v_pk_mul_f32 v[20:21], v[20:21], v[34:35] op_sel_hi:[1,0]
	s_waitcnt vmcnt(0)
	v_pk_mul_f32 v[14:15], v[14:15], v[18:19]
	v_pk_mul_f32 v[16:17], v[16:17], v[20:21]
	v_cvt_pk_bf16_f32 v14, v14, v15
	v_pk_mul_f32 v[18:19], v[22:23], v[34:35] op_sel_hi:[1,0]
	v_cvt_pk_bf16_f32 v15, v16, v17
	global_store_dwordx2 v[2:3], v[14:15], off offset:512
	global_load_dwordx4 v[14:17], v[0:1], off offset:2048
	v_pk_mul_f32 v[20:21], v[24:25], v[34:35] op_sel_hi:[1,0]
	s_waitcnt vmcnt(0)
	v_pk_mul_f32 v[14:15], v[14:15], v[18:19]
	v_pk_mul_f32 v[16:17], v[16:17], v[20:21]
	v_cvt_pk_bf16_f32 v14, v14, v15
	v_pk_mul_f32 v[18:19], v[26:27], v[34:35] op_sel_hi:[1,0]
	v_cvt_pk_bf16_f32 v15, v16, v17
	global_store_dwordx2 v[2:3], v[14:15], off offset:1024
	global_load_dwordx4 v[14:17], v[0:1], off offset:3072
	v_pk_mul_f32 v[20:21], v[28:29], v[34:35] op_sel_hi:[1,0]
	s_waitcnt vmcnt(0)
	v_pk_mul_f32 v[14:15], v[18:19], v[14:15]
	v_pk_mul_f32 v[16:17], v[20:21], v[16:17]
	v_cvt_pk_bf16_f32 v14, v14, v15
	s_nop 0
	v_cvt_pk_bf16_f32 v15, v16, v17
	global_store_dwordx2 v[2:3], v[14:15], off offset:1536
	v_lshl_add_u64 v[2:3], v[2:3], 0, s[4:5]
	s_cbranch_scc0 .LBB0_284
